# v9 with three (instead of two) PV MFMAs per step deferred past the attention step barrier
# speedup vs baseline: 1.0063x; 1.0063x over previous
; #define SBAR() __builtin_amdgcn_sched_barrier(0)
; template <int G> __device__ __forceinline__ void v_load(s16x4& la, s16x4& ha, s16x4& lb, s16x4& hb, const __attribute__((address_space(3))) char* vb) {
;   constexpr int ks = G >> 1, d0 = (G & 1) * 2;
;   la = __builtin_amdgcn_ds_read_tr16_b64_v4i16((lds_s16x4b*)(vb + v_rd_off(d0, ks, 0))); ha = __builtin_amdgcn_ds_read_tr16_b64_v4i16((lds_s16x4b*)(vb + v_rd_off(d0, ks, 1)));
;   lb = __builtin_amdgcn_ds_read_tr16_b64_v4i16((lds_s16x4b*)(vb + v_rd_off(d0 + 1, ks, 0))); hb = __builtin_amdgcn_ds_read_tr16_b64_v4i16((lds_s16x4b*)(vb + v_rd_off(d0 + 1, ks, 1)));
; }
; template <int G> __device__ __forceinline__ void h2_stage(f32x16* o, f32x16& pc0, f32x16& pc1, float& m_reg, float& alC, SMState& st, bf16x8 pa0, bf16x8 pa1, bf16x8 pa2, bf16x8 pa3, ...
;   constexpr int ks = G >> 1, d0 = (G & 1) * 2;
;   s16x4 nla, nha, nlb, nhb;
;   if constexpr (G < 7) v_load<G + 1>(nla, nha, nlb, nhb, vb);
;   const bf16x8 pa = ks == 0 ? pa0 : ks == 1 ? pa1 : ks == 2 ? pa2 : pa3;
;     ...
;   o[d0] = __builtin_amdgcn_mfma_f32_32x32x16_bf16(pa, PK(la, ha), o[d0], 0, 0, 0);
;   o[d0 + 1] = __builtin_amdgcn_mfma_f32_32x32x16_bf16(pa, PK(lb, hb), o[d0 + 1], 0, 0, 0);
;     ...
;   SBAR(); ps_chunk<G>(pc0, pc1, m_reg, alC, st); SBAR();
;   if constexpr (G < 7) h2_stage<G + 1>(o, pc0, pc1, m_reg, alC, st, pa0, pa1, pa2, pa3, nla, nha, nlb, nhb, vb);
; }
.LBB0_657:
	v_exp_f32_e32 v96, v96
	v_exp_f32_e32 v97, v97
	s_waitcnt lgkmcnt(2)
	v_mfma_f32_32x32x16_bf16 v[32:47], v[72:75], v[80:83], v[32:47]
	ds_read_b64_tr_b16 v[80:81], v188 offset:8192
	ds_read_b64_tr_b16 v[82:83], v188 offset:10240
	ds_read_b64_tr_b16 v[86:87], v188 offset:10752
	ds_read_b64_tr_b16 v[84:85], v188 offset:8704
	s_waitcnt lgkmcnt(4)
	v_mfma_f32_32x32x16_bf16 v[16:31], v[72:75], v[76:79], v[16:31]
	v_exp_f32_e32 v98, v98
	v_exp_f32_e32 v99, v99
	v_exp_f32_e32 v100, v100
	s_waitcnt lgkmcnt(2)
	v_mfma_f32_32x32x16_bf16 v[0:15], v[68:71], v[80:83], v[0:15]
	ds_read_b64_tr_b16 v[72:73], v188 offset:9216
	ds_read_b64_tr_b16 v[74:75], v188 offset:11264
	ds_read_b64_tr_b16 v[78:79], v188 offset:11776
	ds_read_b64_tr_b16 v[76:77], v188 offset:9728
	s_waitcnt lgkmcnt(4)
	v_mfma_f32_32x32x16_bf16 v[48:63], v[68:71], v[84:87], v[48:63]
	v_exp_f32_e32 v101, v101
	v_exp_f32_e32 v102, v102
	v_exp_f32_e32 v103, v103
	s_waitcnt lgkmcnt(2)
	v_mfma_f32_32x32x16_bf16 v[32:47], v[68:71], v[72:75], v[32:47]
	ds_read_b64_tr_b16 v[72:73], v188 offset:12288
	ds_read_b64_tr_b16 v[74:75], v188 offset:14336
	ds_read_b64_tr_b16 v[82:83], v188 offset:14848
	ds_read_b64_tr_b16 v[80:81], v188 offset:12800
	s_waitcnt lgkmcnt(4)
	v_mfma_f32_32x32x16_bf16 v[16:31], v[68:71], v[76:79], v[16:31]
	v_exp_f32_e32 v104, v104
	v_exp_f32_e32 v105, v105
	v_exp_f32_e32 v106, v106
	s_waitcnt lgkmcnt(2)
	v_mfma_f32_32x32x16_bf16 v[0:15], v[64:67], v[72:75], v[0:15]
	ds_read_b64_tr_b16 v[68:69], v188 offset:13312
	ds_read_b64_tr_b16 v[70:71], v188 offset:15360
	ds_read_b64_tr_b16 v[74:75], v188 offset:15872
	ds_read_b64_tr_b16 v[72:73], v188 offset:13824
	s_waitcnt lgkmcnt(4)
	v_exp_f32_e32 v107, v107
	v_exp_f32_e32 v108, v108
	v_exp_f32_e32 v109, v109
	s_waitcnt lgkmcnt(0)
	v_exp_f32_e32 v110, v110
	v_exp_f32_e32 v111, v111
	s_waitcnt vmcnt(0)
	v_cmp_gt_f32_e32 vcc, 1.0, v206
	s_cbranch_vccz .Lattn_n1
	v_mfma_f32_32x32x16_bf16 v[48:63], v[64:67], v[80:83], v[48:63]
	v_mfma_f32_32x32x16_bf16 v[32:47], v[64:67], v[68:71], v[32:47]
	v_mfma_f32_32x32x16_bf16 v[16:31], v[64:67], v[72:75], v[16:31]
	s_nop 15
	s_nop 15
	s_and_saveexec_b64 s[10:11], s[4:5]
	ds_write_b32 v189, v206 offset:128
	s_or_b64 exec, exec, s[10:11]
	s_waitcnt lgkmcnt(0)
	v_add_u32_e32 v76, s1, v166
	ds_read_b128 v[64:67], v76 offset:224
	ds_read_b128 v[68:71], v76 offset:192
	ds_read_b128 v[72:75], v76 offset:160
	ds_read_b128 v[76:79], v76 offset:128
	s_waitcnt lgkmcnt(3)
	v_pk_mul_f32 v[12:13], v[12:13], v[64:65]
	s_waitcnt lgkmcnt(2)
	v_pk_mul_f32 v[8:9], v[8:9], v[68:69]
	s_waitcnt lgkmcnt(1)
	v_pk_mul_f32 v[4:5], v[4:5], v[72:73]
	v_pk_mul_f32 v[14:15], v[14:15], v[66:67]
	v_pk_mul_f32 v[10:11], v[10:11], v[70:71]
	v_pk_mul_f32 v[6:7], v[6:7], v[74:75]
	s_waitcnt lgkmcnt(0)
	v_pk_mul_f32 v[2:3], v[2:3], v[78:79]
	v_pk_mul_f32 v[0:1], v[0:1], v[76:77]
	v_pk_mul_f32 v[60:61], v[60:61], v[64:65]
	v_pk_mul_f32 v[56:57], v[56:57], v[68:69]
	v_pk_mul_f32 v[52:53], v[52:53], v[72:73]
	v_pk_mul_f32 v[62:63], v[62:63], v[66:67]
	v_pk_mul_f32 v[58:59], v[58:59], v[70:71]
	v_pk_mul_f32 v[54:55], v[54:55], v[74:75]
	v_pk_mul_f32 v[50:51], v[50:51], v[78:79]
	v_pk_mul_f32 v[48:49], v[48:49], v[76:77]
	v_pk_mul_f32 v[44:45], v[44:45], v[64:65]
	v_pk_mul_f32 v[40:41], v[40:41], v[68:69]
	v_pk_mul_f32 v[36:37], v[36:37], v[72:73]
	v_pk_mul_f32 v[46:47], v[46:47], v[66:67]
	v_pk_mul_f32 v[42:43], v[42:43], v[70:71]
	v_pk_mul_f32 v[38:39], v[38:39], v[74:75]
	v_pk_mul_f32 v[34:35], v[34:35], v[78:79]
	v_pk_mul_f32 v[32:33], v[32:33], v[76:77]
	v_pk_mul_f32 v[28:29], v[28:29], v[64:65]
	v_pk_mul_f32 v[24:25], v[24:25], v[68:69]
	v_pk_mul_f32 v[20:21], v[20:21], v[72:73]
	v_pk_mul_f32 v[30:31], v[30:31], v[66:67]
	v_pk_mul_f32 v[26:27], v[26:27], v[70:71]
	v_pk_mul_f32 v[22:23], v[22:23], v[74:75]
	v_pk_mul_f32 v[18:19], v[18:19], v[78:79]
	v_pk_mul_f32 v[16:17], v[16:17], v[76:77]
	s_waitcnt lgkmcnt(0)
	s_barrier
	v_add_u32_e32 v205, s53, v193
	ds_read_b128 v[208:211], v205 offset:32768
	ds_read_b128 v[212:215], v205 offset:45056
	s_branch .Lattn_m1
.Lattn_n1:
	v_add_u32_e32 v205, s53, v193
	s_waitcnt lgkmcnt(0)
	s_barrier
	ds_read_b128 v[208:211], v205 offset:32768
	ds_read_b128 v[212:215], v205 offset:45056
	v_mfma_f32_32x32x16_bf16 v[48:63], v[64:67], v[80:83], v[48:63]
	v_mfma_f32_32x32x16_bf16 v[32:47], v[64:67], v[68:71], v[32:47]
	v_mfma_f32_32x32x16_bf16 v[16:31], v[64:67], v[72:75], v[16:31]

; #define SBAR() __builtin_amdgcn_sched_barrier(0)
; #define DMAK(t, s) do { dc.gk = (unsigned)((size_t)(t) * TILEB); dc.kd = K_lds + (s) * SHM_K; dma_piece<0>(dc); dma_piece<1>(dc); dma_piece<2>(dc); } while (0)
; #define DMAV(t, s) do { dc.gv = (unsigned)((size_t)(t) * TILEB); dc.vd = V_lds + (s) * SHM_V; dma_piece<3>(dc); dma_piece<4>(dc); } while (0)
; #define BAR() do { asm volatile("s_waitcnt lgkmcnt(0)" ::: "memory"); __builtin_amdgcn_s_barrier(); asm volatile("" ::: "memory"); } while (0)
; template <int G> __device__ __forceinline__ void h2_stage(f32x16* o, f32x16& pc0, f32x16& pc1, float& m_reg, float& alC, SMState& st, bf16x8 pa0, bf16x8 pa1, bf16x8 pa2, bf16x8 pa3, ...
;   constexpr int ks = G >> 1, d0 = (G & 1) * 2;
;   s16x4 nla, nha, nlb, nhb;
;   if constexpr (G < 7) v_load<G + 1>(nla, nha, nlb, nhb, vb);
;   const bf16x8 pa = ks == 0 ? pa0 : ks == 1 ? pa1 : ks == 2 ? pa2 : pa3;
;     ...
;   o[d0] = __builtin_amdgcn_mfma_f32_32x32x16_bf16(pa, PK(la, ha), o[d0], 0, 0, 0);
;   o[d0 + 1] = __builtin_amdgcn_mfma_f32_32x32x16_bf16(pa, PK(lb, hb), o[d0 + 1], 0, 0, 0);
;     ...
;   SBAR(); ps_chunk<G>(pc0, pc1, m_reg, alC, st); SBAR();
;   if constexpr (G < 7) h2_stage<G + 1>(o, pc0, pc1, m_reg, alC, st, pa0, pa1, pa2, pa3, nla, nha, nlb, nhb, vb);
; }
; __device__ __forceinline__ void attn_body(const bf16_t* __restrict__ Qb, const bf16_t* __restrict__ KVb, int hcol, bf16_t* __restrict__ Ob, float* __restrict__ rsqa, int seq, char* lds) {
;     ...
;   f32x16 pA0, pA1, pB0, pB1; float alA, alB; bf16x8 pa0, pa1, pa2, pa3; SMState st; const int NT = seq / KVBLK;
;   DMAK(0, 0); DMAV(0, 0); DMAK(1, 1);
;   asm volatile("s_waitcnt vmcnt(3)" ::: "memory"); BAR();
;   qkt(pA0, pA1, K_lds, qr, qlds, kb); partialSM0(pA0, pA1, m_reg); alA = 1.f;
;   asm volatile("s_waitcnt vmcnt(0)" ::: "memory"); BAR();
;   int sc = 1;
;   for (int j = 1; j + 1 < NT; j += 2) {
;     STEP(pB0, pB1, alB, pA0, pA1, alA, j, sc, 0);
;     sc = NEXT3(sc);
;     STEP(pA0, pA1, alA, pB0, pB1, alB, j + 1, sc, 1);
;     sc = NEXT3(sc);
;   }
.LBB0_662:
	v_exp_f32_e32 v64, v64
	v_exp_f32_e32 v65, v65
	s_waitcnt lgkmcnt(2)
	v_mfma_f32_32x32x16_bf16 v[32:47], v[104:107], v[112:115], v[32:47]
	ds_read_b64_tr_b16 v[112:113], v188 offset:24576
	ds_read_b64_tr_b16 v[114:115], v188 offset:26624
	ds_read_b64_tr_b16 v[120:121], v188 offset:27136
	ds_read_b64_tr_b16 v[118:119], v188 offset:25088
	s_waitcnt lgkmcnt(4)
	v_mfma_f32_32x32x16_bf16 v[16:31], v[104:107], v[108:111], v[16:31]
	v_exp_f32_e32 v66, v66
	v_exp_f32_e32 v67, v67
	v_exp_f32_e32 v68, v68
	s_waitcnt lgkmcnt(2)
	v_mfma_f32_32x32x16_bf16 v[0:15], v[100:103], v[112:115], v[0:15]
	ds_read_b64_tr_b16 v[104:105], v188 offset:25600
	ds_read_b64_tr_b16 v[106:107], v188 offset:27648
	ds_read_b64_tr_b16 v[110:111], v188 offset:28160
	ds_read_b64_tr_b16 v[108:109], v188 offset:26112
	s_waitcnt lgkmcnt(4)
	v_mfma_f32_32x32x16_bf16 v[48:63], v[100:103], v[118:121], v[48:63]
	v_exp_f32_e32 v69, v69
	v_exp_f32_e32 v70, v70
	v_exp_f32_e32 v71, v71
	s_waitcnt lgkmcnt(2)
	v_mfma_f32_32x32x16_bf16 v[32:47], v[100:103], v[104:107], v[32:47]
	ds_read_b64_tr_b16 v[104:105], v188 offset:28672
	ds_read_b64_tr_b16 v[106:107], v188 offset:30720
	ds_read_b64_tr_b16 v[114:115], v188 offset:31232
	ds_read_b64_tr_b16 v[112:113], v188 offset:29184
	s_waitcnt lgkmcnt(4)
	v_mfma_f32_32x32x16_bf16 v[16:31], v[100:103], v[108:111], v[16:31]
	v_exp_f32_e32 v72, v72
	v_exp_f32_e32 v73, v73
	v_exp_f32_e32 v74, v74
	s_waitcnt lgkmcnt(2)
	v_mfma_f32_32x32x16_bf16 v[0:15], v[96:99], v[104:107], v[0:15]
	ds_read_b64_tr_b16 v[100:101], v188 offset:29696
	ds_read_b64_tr_b16 v[102:103], v188 offset:31744
	ds_read_b64_tr_b16 v[106:107], v188 offset:32256
	ds_read_b64_tr_b16 v[104:105], v188 offset:30208
	s_waitcnt lgkmcnt(4)
	v_exp_f32_e32 v75, v75
	v_exp_f32_e32 v76, v76
	v_exp_f32_e32 v77, v77
	s_waitcnt lgkmcnt(0)
	v_exp_f32_e32 v78, v78
	v_exp_f32_e32 v79, v79
	s_waitcnt vmcnt(0)
	v_cmp_gt_f32_e32 vcc, 1.0, v205
	s_cbranch_vccz .Lattn_n2
	v_mfma_f32_32x32x16_bf16 v[48:63], v[96:99], v[112:115], v[48:63]
	v_mfma_f32_32x32x16_bf16 v[32:47], v[96:99], v[100:103], v[32:47]
	v_mfma_f32_32x32x16_bf16 v[16:31], v[96:99], v[104:107], v[16:31]
	s_nop 15
	s_nop 15
	s_and_saveexec_b64 s[10:11], s[4:5]
	ds_write_b32 v189, v205 offset:128
	s_or_b64 exec, exec, s[10:11]
	s_waitcnt lgkmcnt(0)
	v_add_u32_e32 v108, s1, v166
	ds_read_b128 v[96:99], v108 offset:224
	ds_read_b128 v[100:103], v108 offset:192
	ds_read_b128 v[104:107], v108 offset:160
	ds_read_b128 v[108:111], v108 offset:128
	s_waitcnt lgkmcnt(3)
	v_pk_mul_f32 v[12:13], v[12:13], v[96:97]
	s_waitcnt lgkmcnt(2)
	v_pk_mul_f32 v[8:9], v[8:9], v[100:101]
	s_waitcnt lgkmcnt(1)
	v_pk_mul_f32 v[4:5], v[4:5], v[104:105]
	v_pk_mul_f32 v[14:15], v[14:15], v[98:99]
	v_pk_mul_f32 v[10:11], v[10:11], v[102:103]
	v_pk_mul_f32 v[6:7], v[6:7], v[106:107]
	s_waitcnt lgkmcnt(0)
	v_pk_mul_f32 v[2:3], v[2:3], v[110:111]
	v_pk_mul_f32 v[0:1], v[0:1], v[108:109]
	v_pk_mul_f32 v[60:61], v[60:61], v[96:97]
	v_pk_mul_f32 v[56:57], v[56:57], v[100:101]
	v_pk_mul_f32 v[52:53], v[52:53], v[104:105]
	v_pk_mul_f32 v[62:63], v[62:63], v[98:99]
	v_pk_mul_f32 v[58:59], v[58:59], v[102:103]
	v_pk_mul_f32 v[54:55], v[54:55], v[106:107]
	v_pk_mul_f32 v[50:51], v[50:51], v[110:111]
	v_pk_mul_f32 v[48:49], v[48:49], v[108:109]
	v_pk_mul_f32 v[44:45], v[44:45], v[96:97]
	v_pk_mul_f32 v[40:41], v[40:41], v[100:101]
	v_pk_mul_f32 v[36:37], v[36:37], v[104:105]
	v_pk_mul_f32 v[46:47], v[46:47], v[98:99]
	v_pk_mul_f32 v[42:43], v[42:43], v[102:103]
	v_pk_mul_f32 v[38:39], v[38:39], v[106:107]
	v_pk_mul_f32 v[34:35], v[34:35], v[110:111]
	v_pk_mul_f32 v[32:33], v[32:33], v[108:109]
	v_pk_mul_f32 v[28:29], v[28:29], v[96:97]
	v_pk_mul_f32 v[24:25], v[24:25], v[100:101]
	v_pk_mul_f32 v[20:21], v[20:21], v[104:105]
	v_pk_mul_f32 v[30:31], v[30:31], v[98:99]
	v_pk_mul_f32 v[26:27], v[26:27], v[102:103]
	v_pk_mul_f32 v[22:23], v[22:23], v[106:107]
	v_pk_mul_f32 v[18:19], v[18:19], v[110:111]
	v_pk_mul_f32 v[16:17], v[16:17], v[108:109]
	v_add_f32_e32 v243, v203, v204
	v_fmac_f32_e32 v243, v190, v202
	v_add_f32_e32 v190, v116, v117
	v_fmac_f32_e32 v190, v243, v206
	v_mov_b32_e32 v202, v205
	s_add_i32 s51, s51, 0x84000
	s_add_i32 s72, s72, 2
	s_mul_i32 s98, s73, 0x6000
	v_add_u32_e32 v203, s98, v193
	s_waitcnt lgkmcnt(0)
	s_barrier
	s_cmp_ge_u32 s72, s37
	s_cbranch_scc1 .LBB0_670
	ds_read_b128 v[204:207], v203 offset:32768
	ds_read_b128 v[208:211], v203 offset:45056
	s_add_i32 s10, s73, 1
	s_cmp_lg_u32 s73, 2
	s_cselect_b32 s52, s10, 0
	s_mov_b32 s10, s98
	s_branch .Lattn_m2
.Lattn_n2:
	v_add_f32_e32 v243, v203, v204
	v_fmac_f32_e32 v243, v190, v202
	v_add_f32_e32 v190, v116, v117
	v_fmac_f32_e32 v190, v243, v206
	v_mov_b32_e32 v202, v205
	s_add_i32 s51, s51, 0x84000
	s_add_i32 s72, s72, 2
	s_mul_i32 s98, s73, 0x6000
	v_add_u32_e32 v203, s98, v193
	s_waitcnt lgkmcnt(0)
	s_barrier
	s_cmp_ge_u32 s72, s37
	s_cbranch_scc1 .Lattn_tdef
	ds_read_b128 v[204:207], v203 offset:32768
	ds_read_b128 v[208:211], v203 offset:45056
	v_mfma_f32_32x32x16_bf16 v[48:63], v[96:99], v[112:115], v[48:63]
	v_mfma_f32_32x32x16_bf16 v[32:47], v[96:99], v[100:103], v[32:47]
	v_mfma_f32_32x32x16_bf16 v[16:31], v[96:99], v[104:107], v[16:31]
	s_add_i32 s10, s73, 1
	s_cmp_lg_u32 s73, 2
	s_cselect_b32 s52, s10, 0
	s_mov_b32 s10, s98
	s_branch .Lattn_m2

; template <int G> __device__ __forceinline__ void h2_stage(f32x16* o, f32x16& pc0, f32x16& pc1, float& m_reg, float& alC, SMState& st, bf16x8 pa0, bf16x8 pa1, bf16x8 pa2, bf16x8 pa3, ...
;     ...
;   const bf16x8 pa = ks == 0 ? pa0 : ks == 1 ? pa1 : ks == 2 ? pa2 : pa3;
;     ...
;   o[d0] = __builtin_amdgcn_mfma_f32_32x32x16_bf16(pa, PK(la, ha), o[d0], 0, 0, 0);
;   o[d0 + 1] = __builtin_amdgcn_mfma_f32_32x32x16_bf16(pa, PK(lb, hb), o[d0 + 1], 0, 0, 0);
.Lattn_tdef:
	v_mfma_f32_32x32x16_bf16 v[48:63], v[96:99], v[112:115], v[48:63]
	v_mfma_f32_32x32x16_bf16 v[32:47], v[96:99], v[100:103], v[32:47]
	v_mfma_f32_32x32x16_bf16 v[16:31], v[96:99], v[104:107], v[16:31]
